# v031 + system-scope (sc0 sc1) bits on the S5 context-task operand loads (no timing effect expected)
# speedup vs baseline: 1.1999x; 1.0190x over previous
.LBB0_719:
	s_and_b32 s19, s18, 7
	s_ashr_i32 s8, s18, 3
	s_lshr_b32 s6, s8, 3
	s_lshl_b32 s9, s19, 3
	s_add_i32 s9, s9, s6
	s_and_b32 s6, s8, 7
	v_readlane_b32 s20, v253, 1
	s_nop 0
	s_cmpk_eq_i32 s20, 0x200
	s_cselect_b32 s8, s9, s8
	s_cselect_b32 s19, s6, s19
	s_mov_b32 s6, s19
	s_mul_i32 s22, s8, 0x108000
	s_mul_i32 s20, s6, 0xb0000
	s_mul_hi_i32 s21, s8, 0x108000
	s_add_u32 s6, s14, s22
	s_addc_u32 s7, s15, s21
	s_mul_i32 s9, s19, 0xb0000
	s_add_u32 s12, s16, s9
	s_addc_u32 s13, s17, 0
	v_mov_b32_e32 v16, v196
	v_mov_b64_e32 v[2:3], s[6:7]
	v_ashrrev_i32_e32 v17, 3, v16
	s_movk_i32 s23, 0x1600
	v_lshlrev_b32_e32 v0, 4, v16
	v_mov_b64_e32 v[8:9], s[12:13]
	v_mad_i64_i32 v[2:3], s[6:7], v17, s23, v[2:3]
	v_and_b32_e32 v10, 0x70, v0
	v_mov_b32_e32 v11, v1
	v_mad_i64_i32 v[8:9], s[6:7], v17, s23, v[8:9]
	v_lshl_add_u64 v[2:3], v[2:3], 0, v[10:11]
	s_mov_b32 s7, 0x2c000
	v_add_co_u32_e32 v12, vcc, s7, v2
	s_mov_b32 s12, 0x58000
	s_nop 0
	v_addc_co_u32_e32 v13, vcc, 0, v3, vcc
	global_load_dwordx4 v[100:103], v[2:3], off
	global_load_dwordx4 v[104:107], v[12:13], off
	v_add_co_u32_e32 v12, vcc, s12, v2
	s_mov_b32 s13, 0x84000
	s_nop 0
	v_addc_co_u32_e32 v13, vcc, 0, v3, vcc
	v_add_co_u32_e32 v14, vcc, s13, v2
	s_mov_b32 s6, 0xb0000
	s_nop 0
	v_addc_co_u32_e32 v15, vcc, 0, v3, vcc
	global_load_dwordx4 v[108:111], v[12:13], off
	global_load_dwordx4 v[112:115], v[14:15], off
	v_add_co_u32_e32 v12, vcc, s6, v2
	s_mov_b32 s6, 0xdc000
	s_nop 0
	v_addc_co_u32_e32 v13, vcc, 0, v3, vcc
	v_add_co_u32_e32 v2, vcc, s6, v2
	v_and_b32_e32 v0, 15, v16
	s_nop 0
	v_addc_co_u32_e32 v3, vcc, 0, v3, vcc
	global_load_dwordx4 v[116:119], v[12:13], off
	global_load_dwordx4 v[120:123], v[2:3], off
	v_lshl_add_u64 v[2:3], v[8:9], 0, v[10:11]
	v_add_co_u32_e32 v8, vcc, s7, v2
	v_mul_lo_u32 v11, v17, s33
	s_nop 0
	v_addc_co_u32_e32 v9, vcc, 0, v3, vcc
	global_load_dwordx4 v[124:127], v[2:3], off
	global_load_dwordx4 v[128:131], v[8:9], off
	v_add_co_u32_e32 v8, vcc, s12, v2
	s_mov_b32 s9, 0
	s_nop 0
	v_addc_co_u32_e32 v9, vcc, 0, v3, vcc
	v_add_co_u32_e32 v2, vcc, s13, v2
	s_waitcnt vmcnt(16)
	v_add_u32_e32 v148, v10, v11
	v_addc_co_u32_e32 v3, vcc, 0, v3, vcc
	global_load_dwordx4 v[136:139], v[8:9], off
	global_load_dwordx4 v[140:143], v[2:3], off
	v_and_or_b32 v2, v17, s11, v0
	v_and_b32_e32 v0, 48, v16
	v_mad_u64_u32 v[2:3], s[6:7], v2, s33, v[0:1]
	s_add_u32 s6, s2, s20
	s_addc_u32 s7, s3, 0
	v_mov_b64_e32 v[8:9], s[6:7]
	v_mad_i64_i32 v[144:145], s[6:7], v17, s23, v[8:9]
	s_add_u32 s6, s0, s22
	s_addc_u32 s7, s1, s21
	v_and_b32_e32 v3, 0x4f, v16
	v_mov_b64_e32 v[8:9], s[6:7]
	v_mad_u32_u24 v3, v3, s33, v0
	v_and_b32_e32 v0, 7, v16
	v_mad_i64_i32 v[146:147], s[6:7], v17, s23, v[8:9]
	v_mov_b32_e32 v8, 0
	v_lshlrev_b32_e32 v0, 4, v0
	v_mov_b32_e32 v9, v8
	v_mov_b32_e32 v10, v8
	v_mov_b32_e32 v11, v8
	v_mov_b32_e32 v12, v8
	v_mov_b32_e32 v13, v8
	v_mov_b32_e32 v14, v8
	v_mov_b32_e32 v15, v8
	v_mov_b32_e32 v16, v8
	v_mov_b32_e32 v17, v8
	v_mov_b32_e32 v18, v8
	v_mov_b32_e32 v19, v8
	v_mov_b32_e32 v20, v8
	v_mov_b32_e32 v21, v8
	v_mov_b32_e32 v22, v8
	v_mov_b32_e32 v23, v8
	v_mov_b32_e32 v24, v8
	v_mov_b32_e32 v25, v8
	v_mov_b32_e32 v26, v8
	v_mov_b32_e32 v27, v8
	v_mov_b32_e32 v28, v8
	v_mov_b32_e32 v29, v8
	v_mov_b32_e32 v30, v8
	v_mov_b32_e32 v31, v8
	v_mov_b32_e32 v32, v8
	v_mov_b32_e32 v33, v8
	v_mov_b32_e32 v34, v8
	v_mov_b32_e32 v35, v8
	v_mov_b32_e32 v36, v8
	v_mov_b32_e32 v37, v8
	v_mov_b32_e32 v38, v8
	v_mov_b32_e32 v39, v8
	v_mov_b32_e32 v40, v8
	v_mov_b32_e32 v41, v8
	v_mov_b32_e32 v42, v8
	v_mov_b32_e32 v43, v8
	v_mov_b32_e32 v44, v8
	v_mov_b32_e32 v45, v8
	v_mov_b32_e32 v46, v8
	v_mov_b32_e32 v47, v8
	v_mov_b32_e32 v48, v8
	v_mov_b32_e32 v49, v8
	v_mov_b32_e32 v50, v8
	v_mov_b32_e32 v51, v8
	v_mov_b32_e32 v52, v8
	v_mov_b32_e32 v53, v8
	v_mov_b32_e32 v54, v8
	v_mov_b32_e32 v55, v8
	s_waitcnt vmcnt(10)
	v_mov_b32_e32 v56, v8
	v_mov_b32_e32 v57, v8
	v_mov_b32_e32 v58, v8
	v_mov_b32_e32 v59, v8
	v_mov_b32_e32 v60, v8
	v_mov_b32_e32 v61, v8
	v_mov_b32_e32 v62, v8
	v_mov_b32_e32 v63, v8
	v_mov_b32_e32 v64, v8
	v_mov_b32_e32 v65, v8
	v_mov_b32_e32 v66, v8
	v_mov_b32_e32 v67, v8
	v_mov_b32_e32 v68, v8
	v_mov_b32_e32 v69, v8
	v_mov_b32_e32 v70, v8
	v_mov_b32_e32 v71, v8
	v_mov_b32_e32 v72, v8
	v_mov_b32_e32 v73, v8
	v_mov_b32_e32 v74, v8
	v_mov_b32_e32 v75, v8
	v_mov_b32_e32 v76, v8
	v_mov_b32_e32 v77, v8
	v_mov_b32_e32 v78, v8
	v_mov_b32_e32 v79, v8
	v_mov_b32_e32 v80, v8
	v_mov_b32_e32 v81, v8
	v_mov_b32_e32 v82, v8
	v_mov_b32_e32 v83, v8
	v_mov_b32_e32 v84, v8
	v_mov_b32_e32 v85, v8
	v_mov_b32_e32 v86, v8
	v_mov_b32_e32 v87, v8
	v_mov_b32_e32 v88, v8
	v_mov_b32_e32 v89, v8
	v_mov_b32_e32 v90, v8
	v_mov_b32_e32 v91, v8
	v_mov_b32_e32 v92, v8
	v_mov_b32_e32 v93, v8
	v_mov_b32_e32 v94, v8
	v_mov_b32_e32 v95, v8
	v_mov_b32_e32 v96, v8
	v_mov_b32_e32 v97, v8
	v_mov_b32_e32 v98, v8
	v_mov_b32_e32 v99, v8
	v_mov_b32_e32 v132, v8
	v_mov_b32_e32 v133, v8
	v_mov_b32_e32 v134, v8
	v_mov_b32_e32 v135, v8
	s_branch .LBB0_721

.LBB0_748:
	s_and_b32 s2, s16, 7
	s_ashr_i32 s3, s16, 3
	s_lshr_b32 s0, s3, 3
	s_lshl_b32 s17, s2, 3
	s_add_i32 s17, s17, s0
	s_and_b32 s0, s3, 7
	v_readlane_b32 s18, v253, 1
	s_nop 0
	s_cmpk_eq_i32 s18, 0x200
	s_cselect_b32 s3, s17, s3
	s_cselect_b32 s2, s0, s2
	s_mov_b32 s0, s2
	v_mov_b32_e32 v20, v196
	s_lshl_b32 s17, s0, 18
	s_mul_i32 s19, s3, 0x60000
	s_mul_hi_i32 s18, s3, 0x60000
	v_ashrrev_i32_e32 v8, 3, v20
	s_add_u32 s0, s12, s19
	v_ashrrev_i32_e32 v9, 31, v8
	s_addc_u32 s1, s13, s18
	v_lshlrev_b64 v[10:11], 11, v[8:9]
	v_lshlrev_b32_e32 v0, 4, v20
	v_lshl_add_u64 v[2:3], s[0:1], 0, v[10:11]
	v_and_b32_e32 v12, 0x70, v0
	v_mov_b32_e32 v13, v1
	v_lshl_add_u64 v[2:3], v[2:3], 0, v[12:13]
	s_mov_b32 s0, 0x10000
	s_lshl_b32 s8, s2, 18
	v_add_co_u32_e32 v16, vcc, s0, v2
	s_add_u32 s8, s14, s8
	s_nop 0
	v_addc_co_u32_e32 v17, vcc, 0, v3, vcc
	s_mov_b32 s1, 0x20000
	s_addc_u32 s9, s15, 0
	global_load_dwordx4 v[104:107], v[2:3], off
	global_load_dwordx4 v[108:111], v[16:17], off
	v_add_co_u32_e32 v16, vcc, s1, v2
	v_lshl_add_u64 v[14:15], s[8:9], 0, v[10:11]
	s_nop 0
	v_addc_co_u32_e32 v17, vcc, 0, v3, vcc
	s_mov_b32 s9, 0x30000
	v_add_co_u32_e32 v18, vcc, s9, v2
	s_mov_b32 s20, 0x40000
	s_nop 0
	v_addc_co_u32_e32 v19, vcc, 0, v3, vcc
	global_load_dwordx4 v[112:115], v[16:17], off
	global_load_dwordx4 v[116:119], v[18:19], off
	v_add_co_u32_e32 v16, vcc, s20, v2
	s_mov_b32 s20, 0x50000
	s_nop 0
	v_addc_co_u32_e32 v17, vcc, 0, v3, vcc
	v_add_co_u32_e32 v2, vcc, s20, v2
	v_and_b32_e32 v0, 15, v20
	s_nop 0
	v_addc_co_u32_e32 v3, vcc, 0, v3, vcc
	global_load_dwordx4 v[120:123], v[16:17], off
	global_load_dwordx4 v[124:127], v[2:3], off
	v_lshl_add_u64 v[2:3], v[14:15], 0, v[12:13]
	v_add_co_u32_e32 v14, vcc, s0, v2
	v_mul_lo_u32 v9, v8, s33
	s_nop 0
	v_addc_co_u32_e32 v15, vcc, 0, v3, vcc
	global_load_dwordx4 v[128:131], v[2:3], off
	global_load_dwordx4 v[132:135], v[14:15], off
	v_add_co_u32_e32 v14, vcc, s1, v2
	s_mov_b32 s8, 0
	s_nop 0
	v_addc_co_u32_e32 v15, vcc, 0, v3, vcc
	v_add_co_u32_e32 v2, vcc, s9, v2
	s_waitcnt vmcnt(16)
	v_add_u32_e32 v148, v12, v9
	v_addc_co_u32_e32 v3, vcc, 0, v3, vcc
	global_load_dwordx4 v[136:139], v[14:15], off
	global_load_dwordx4 v[140:143], v[2:3], off
	v_and_or_b32 v2, v8, s11, v0
	v_and_b32_e32 v0, 48, v20
	v_mad_u64_u32 v[2:3], s[0:1], v2, s33, v[0:1]
	s_add_u32 s0, s40, s17
	s_addc_u32 s1, s41, 0
	v_and_b32_e32 v3, 0x4f, v20
	v_lshl_add_u64 v[144:145], s[0:1], 0, v[10:11]
	s_add_u32 s0, s6, s19
	v_mad_u32_u24 v3, v3, s33, v0
	v_and_b32_e32 v0, 7, v20
	s_addc_u32 s1, s7, s18
	v_mov_b32_e32 v8, 0
	v_lshlrev_b32_e32 v0, 4, v0
	v_lshl_add_u64 v[146:147], s[0:1], 0, v[10:11]
	v_mov_b32_e32 v9, v8
	v_mov_b32_e32 v10, v8
	v_mov_b32_e32 v11, v8
	v_mov_b32_e32 v12, v8
	v_mov_b32_e32 v13, v8
	v_mov_b32_e32 v14, v8
	v_mov_b32_e32 v15, v8
	v_mov_b32_e32 v16, v8
	v_mov_b32_e32 v17, v8
	v_mov_b32_e32 v18, v8
	v_mov_b32_e32 v19, v8
	v_mov_b32_e32 v20, v8
	v_mov_b32_e32 v21, v8
	v_mov_b32_e32 v22, v8
	v_mov_b32_e32 v23, v8
	v_mov_b32_e32 v24, v8
	v_mov_b32_e32 v25, v8
	v_mov_b32_e32 v26, v8
	v_mov_b32_e32 v27, v8
	v_mov_b32_e32 v28, v8
	v_mov_b32_e32 v29, v8
	v_mov_b32_e32 v30, v8
	v_mov_b32_e32 v31, v8
	v_mov_b32_e32 v32, v8
	v_mov_b32_e32 v33, v8
	v_mov_b32_e32 v34, v8
	v_mov_b32_e32 v35, v8
	v_mov_b32_e32 v36, v8
	v_mov_b32_e32 v37, v8
	v_mov_b32_e32 v38, v8
	v_mov_b32_e32 v39, v8
	v_mov_b32_e32 v40, v8
	v_mov_b32_e32 v41, v8
	v_mov_b32_e32 v42, v8
	v_mov_b32_e32 v43, v8
	v_mov_b32_e32 v44, v8
	v_mov_b32_e32 v45, v8
	v_mov_b32_e32 v46, v8
	v_mov_b32_e32 v47, v8
	v_mov_b32_e32 v48, v8
	v_mov_b32_e32 v49, v8
	v_mov_b32_e32 v50, v8
	v_mov_b32_e32 v51, v8
	v_mov_b32_e32 v52, v8
	v_mov_b32_e32 v53, v8
	v_mov_b32_e32 v54, v8
	v_mov_b32_e32 v55, v8
	s_waitcnt vmcnt(10)
	v_mov_b32_e32 v56, v8
	v_mov_b32_e32 v57, v8
	v_mov_b32_e32 v58, v8
	v_mov_b32_e32 v59, v8
	v_mov_b32_e32 v60, v8
	v_mov_b32_e32 v61, v8
	v_mov_b32_e32 v62, v8
	v_mov_b32_e32 v63, v8
	v_mov_b32_e32 v64, v8
	v_mov_b32_e32 v65, v8
	v_mov_b32_e32 v66, v8
	v_mov_b32_e32 v67, v8
	v_mov_b32_e32 v68, v8
	v_mov_b32_e32 v69, v8
	v_mov_b32_e32 v70, v8
	v_mov_b32_e32 v71, v8
	v_mov_b32_e32 v72, v8
	v_mov_b32_e32 v73, v8
	v_mov_b32_e32 v74, v8
	v_mov_b32_e32 v75, v8
	v_mov_b32_e32 v76, v8
	v_mov_b32_e32 v77, v8
	v_mov_b32_e32 v78, v8
	v_mov_b32_e32 v79, v8
	v_mov_b32_e32 v80, v8
	v_mov_b32_e32 v81, v8
	v_mov_b32_e32 v82, v8
	v_mov_b32_e32 v83, v8
	v_mov_b32_e32 v84, v8
	v_mov_b32_e32 v85, v8
	v_mov_b32_e32 v86, v8
	v_mov_b32_e32 v87, v8
	v_mov_b32_e32 v88, v8
	v_mov_b32_e32 v89, v8
	v_mov_b32_e32 v90, v8
	v_mov_b32_e32 v91, v8
	v_mov_b32_e32 v92, v8
	v_mov_b32_e32 v93, v8
	v_mov_b32_e32 v94, v8
	v_mov_b32_e32 v95, v8
	v_mov_b32_e32 v96, v8
	v_mov_b32_e32 v97, v8
	v_mov_b32_e32 v98, v8
	v_mov_b32_e32 v99, v8
	v_mov_b32_e32 v100, v8
	v_mov_b32_e32 v101, v8
	v_mov_b32_e32 v102, v8
	v_mov_b32_e32 v103, v8
	s_branch .LBB0_750

.LBB0_1606:
	s_or_b32 s16, s4, s3
	s_mov_b64 s[12:13], s[62:63]
	s_ashr_i32 s17, s16, 31
	s_lshl_b64 s[16:17], s[16:17], 15
	s_add_u32 s12, s12, s16
	s_addc_u32 s13, s13, s17
	v_lshl_add_u64 v[2:3], s[12:13], 0, v[0:1]
	s_mov_b64 s[12:13], 0xe454000
	v_lshl_add_u64 v[2:3], v[2:3], 0, s[12:13]
	v_lshl_add_u64 v[96:97], v[2:3], 0, v[56:57]
	s_barrier
	global_load_dwordx4 v[146:149], v[96:97], off
	v_lshl_add_u64 v[96:97], v[2:3], 0, v[58:59]
	v_cndmask_b32_e64 v94, v113, v112, s[8:9]
	s_mov_b32 s4, 4
	s_and_b64 vcc, exec, s[8:9]
	global_load_dwordx4 v[150:153], v[96:97], off
	v_lshl_add_u64 v[96:97], v[2:3], 0, v[60:61]
	global_load_dwordx4 v[154:157], v[96:97], off
	v_lshl_add_u64 v[96:97], v[2:3], 0, v[62:63]
	global_load_dwordx4 v[158:161], v[96:97], off
	v_lshl_add_u64 v[96:97], v[2:3], 0, v[64:65]
	global_load_dwordx4 v[162:165], v[96:97], off
	v_lshl_add_u64 v[96:97], v[2:3], 0, v[66:67]
	global_load_dwordx4 v[166:169], v[96:97], off
	v_lshl_add_u64 v[96:97], v[2:3], 0, v[68:69]
	v_lshl_add_u64 v[2:3], v[2:3], 0, v[70:71]
	global_load_dwordx4 v[170:173], v[96:97], off
	v_cndmask_b32_e64 v96, v81, v82, s[8:9]
	global_load_dwordx4 v[174:177], v[2:3], off
	v_cndmask_b32_e64 v3, v76, v88, s[8:9]
	v_cvt_f32_i32_e32 v3, v3
	v_cndmask_b32_e64 v2, v77, v78, s[8:9]
	v_mul_f32_e32 v3, v94, v3
	v_mul_f32_e32 v3, 0x3fb8aa3b, v3
	v_exp_f32_e32 v3, v3
	v_cndmask_b32_e64 v94, v79, v80, s[8:9]
	s_mov_b64 s[8:9], 0
	s_waitcnt vmcnt(7)
	ds_write_b128 v114, v[146:149]
	s_waitcnt vmcnt(6)
	ds_write_b128 v83, v[150:153]
	s_waitcnt vmcnt(5)
	ds_write_b128 v84, v[154:157]
	s_waitcnt vmcnt(4)
	ds_write_b128 v85, v[158:161]
	s_waitcnt vmcnt(3)
	ds_write_b128 v86, v[162:165]
	s_waitcnt vmcnt(2)
	ds_write_b128 v87, v[166:169]
	s_waitcnt vmcnt(1)
	ds_write_b128 v89, v[170:173]
	s_waitcnt vmcnt(0)
	ds_write_b128 v90, v[174:177]
	s_waitcnt lgkmcnt(0)
	s_barrier
	ds_read_b128 v[100:103], v91
	ds_read_b128 v[104:107], v91 offset:64
	s_waitcnt lgkmcnt(1)
	v_mfma_f32_16x16x32_bf16 v[100:103], v[40:43], v[100:103], 0
	s_waitcnt lgkmcnt(0)
	v_mfma_f32_16x16x32_bf16 v[100:103], v[44:47], v[104:107], v[100:103]
	ds_read_b128 v[104:107], v91 offset:128
	s_waitcnt lgkmcnt(0)
	v_mfma_f32_16x16x32_bf16 v[100:103], v[48:51], v[104:107], v[100:103]
	ds_read_b128 v[104:107], v91 offset:192
	s_waitcnt lgkmcnt(0)
	v_mfma_f32_16x16x32_bf16 v[100:103], v[52:55], v[104:107], v[100:103]
	ds_read_b128 v[104:107], v92 offset:64
	s_nop 6
	v_pk_fma_f32 v[8:9], v[2:3], v[100:101], v[8:9]
	v_fmac_f32_e32 v10, v94, v102
	v_fmac_f32_e32 v11, v96, v103
	ds_read_b128 v[100:103], v92
	s_waitcnt lgkmcnt(0)
	v_mfma_f32_16x16x32_bf16 v[100:103], v[40:43], v[100:103], 0
	v_mfma_f32_16x16x32_bf16 v[100:103], v[44:47], v[104:107], v[100:103]
	ds_read_b128 v[104:107], v92 offset:128
	s_waitcnt lgkmcnt(0)
	v_mfma_f32_16x16x32_bf16 v[100:103], v[48:51], v[104:107], v[100:103]
	ds_read_b128 v[104:107], v92 offset:192
	s_waitcnt lgkmcnt(0)
	v_mfma_f32_16x16x32_bf16 v[100:103], v[52:55], v[104:107], v[100:103]
	ds_read_b128 v[104:107], v92 offset:4416
	s_nop 6
	v_pk_fma_f32 v[16:17], v[2:3], v[100:101], v[16:17]
	v_fmac_f32_e32 v18, v94, v102
	v_fmac_f32_e32 v19, v96, v103
	ds_read_b128 v[100:103], v92 offset:4352
	s_waitcnt lgkmcnt(0)
	v_mfma_f32_16x16x32_bf16 v[100:103], v[40:43], v[100:103], 0
	v_mfma_f32_16x16x32_bf16 v[100:103], v[44:47], v[104:107], v[100:103]
	ds_read_b128 v[104:107], v92 offset:4480
	s_waitcnt lgkmcnt(0)
	v_mfma_f32_16x16x32_bf16 v[100:103], v[48:51], v[104:107], v[100:103]
	ds_read_b128 v[104:107], v92 offset:4544
	s_waitcnt lgkmcnt(0)
	v_mfma_f32_16x16x32_bf16 v[100:103], v[52:55], v[104:107], v[100:103]
	ds_read_b128 v[104:107], v92 offset:8768
	s_nop 6
	v_pk_fma_f32 v[12:13], v[2:3], v[100:101], v[12:13]
	v_fmac_f32_e32 v14, v94, v102
	v_fmac_f32_e32 v15, v96, v103
	ds_read_b128 v[100:103], v92 offset:8704
	s_waitcnt lgkmcnt(0)
	v_mfma_f32_16x16x32_bf16 v[100:103], v[40:43], v[100:103], 0
	v_mfma_f32_16x16x32_bf16 v[100:103], v[44:47], v[104:107], v[100:103]
	ds_read_b128 v[104:107], v92 offset:8832
	s_waitcnt lgkmcnt(0)
	v_mfma_f32_16x16x32_bf16 v[100:103], v[48:51], v[104:107], v[100:103]
	ds_read_b128 v[104:107], v92 offset:8896
	s_waitcnt lgkmcnt(0)
	v_mfma_f32_16x16x32_bf16 v[100:103], v[52:55], v[104:107], v[100:103]
	ds_read_b128 v[104:107], v92 offset:13120
	s_nop 6
	v_pk_fma_f32 v[36:37], v[2:3], v[100:101], v[36:37]
	v_fmac_f32_e32 v38, v94, v102
	v_fmac_f32_e32 v39, v96, v103
	ds_read_b128 v[100:103], v92 offset:13056
	s_waitcnt lgkmcnt(0)
	v_mfma_f32_16x16x32_bf16 v[100:103], v[40:43], v[100:103], 0
	v_mfma_f32_16x16x32_bf16 v[100:103], v[44:47], v[104:107], v[100:103]
	ds_read_b128 v[104:107], v92 offset:13184
	s_waitcnt lgkmcnt(0)
	v_mfma_f32_16x16x32_bf16 v[100:103], v[48:51], v[104:107], v[100:103]
	ds_read_b128 v[104:107], v92 offset:13248
	s_waitcnt lgkmcnt(0)
	v_mfma_f32_16x16x32_bf16 v[100:103], v[52:55], v[104:107], v[100:103]
	ds_read_b128 v[104:107], v92 offset:17472
	s_nop 6
	v_pk_fma_f32 v[20:21], v[2:3], v[100:101], v[20:21]
	v_fmac_f32_e32 v22, v94, v102
	v_fmac_f32_e32 v23, v96, v103
	ds_read_b128 v[100:103], v92 offset:17408
	s_waitcnt lgkmcnt(0)
	v_mfma_f32_16x16x32_bf16 v[100:103], v[40:43], v[100:103], 0
	v_mfma_f32_16x16x32_bf16 v[100:103], v[44:47], v[104:107], v[100:103]
	ds_read_b128 v[104:107], v92 offset:17536
	s_waitcnt lgkmcnt(0)
	v_mfma_f32_16x16x32_bf16 v[100:103], v[48:51], v[104:107], v[100:103]
	ds_read_b128 v[104:107], v92 offset:17600
	s_waitcnt lgkmcnt(0)
	v_mfma_f32_16x16x32_bf16 v[100:103], v[52:55], v[104:107], v[100:103]
	ds_read_b128 v[104:107], v92 offset:21824
	s_nop 6
	v_pk_fma_f32 v[32:33], v[2:3], v[100:101], v[32:33]
	v_fmac_f32_e32 v34, v94, v102
	v_fmac_f32_e32 v35, v96, v103
	ds_read_b128 v[100:103], v92 offset:21760
	s_waitcnt lgkmcnt(0)
	v_mfma_f32_16x16x32_bf16 v[100:103], v[40:43], v[100:103], 0
	v_mfma_f32_16x16x32_bf16 v[100:103], v[44:47], v[104:107], v[100:103]
	ds_read_b128 v[104:107], v92 offset:21888
	s_waitcnt lgkmcnt(0)
	v_mfma_f32_16x16x32_bf16 v[100:103], v[48:51], v[104:107], v[100:103]
	ds_read_b128 v[104:107], v92 offset:21952
	s_waitcnt lgkmcnt(0)
	v_mfma_f32_16x16x32_bf16 v[100:103], v[52:55], v[104:107], v[100:103]
	ds_read_b128 v[104:107], v92 offset:26176
	s_nop 6
	v_pk_fma_f32 v[24:25], v[2:3], v[100:101], v[24:25]
	v_fmac_f32_e32 v26, v94, v102
	v_fmac_f32_e32 v27, v96, v103
	ds_read_b128 v[100:103], v92 offset:26112
	s_waitcnt lgkmcnt(0)
	v_mfma_f32_16x16x32_bf16 v[100:103], v[40:43], v[100:103], 0
	v_mfma_f32_16x16x32_bf16 v[100:103], v[44:47], v[104:107], v[100:103]
	ds_read_b128 v[104:107], v92 offset:26240
	s_waitcnt lgkmcnt(0)
	v_mfma_f32_16x16x32_bf16 v[100:103], v[48:51], v[104:107], v[100:103]
	ds_read_b128 v[104:107], v92 offset:26304
	s_waitcnt lgkmcnt(0)
	v_mfma_f32_16x16x32_bf16 v[100:103], v[52:55], v[104:107], v[100:103]
	s_nop 7
	v_pk_fma_f32 v[28:29], v[2:3], v[100:101], v[28:29]
	v_fmac_f32_e32 v30, v94, v102
	v_fmac_f32_e32 v31, v96, v103
	s_cbranch_vccnz .LBB0_1606
	v_mov_b32_e32 v48, v72
	v_mov_b32_e32 v46, v73
	v_mov_b32_e32 v44, v74
	v_mov_b32_e32 v42, v75
	s_branch .LBB0_1583

.LBB0_1744:
	s_or_b64 exec, exec, s[0:1]
	s_waitcnt lgkmcnt(0)
	s_barrier
	ds_read_b32 v0, v1 offset:58392
	v_readlane_b32 s0, v253, 63
	s_waitcnt lgkmcnt(0)
	v_readfirstlane_b32 s4, v0
	v_cmp_le_i32_e32 vcc, s0, v0
	s_mov_b64 s[0:1], -1
	s_cbranch_vccnz .LBB0_1739
	v_mov_b32_e32 v3, v196
	s_lshl_b32 s0, s4, 1
	v_ashrrev_i32_e32 v66, 6, v3
	s_and_b32 s0, s0, 30
	v_ashrrev_i32_e32 v0, 7, v3
	v_and_b32_e32 v114, 1, v66
	v_add_u32_e32 v2, s0, v0
	v_lshlrev_b32_e32 v0, 5, v114
	v_readlane_b32 s0, v255, 17
	s_mov_b64 s[12:13], s[62:63]
	s_mov_b64 s[8:9], s[62:63]
	v_add3_u32 v40, v2, s0, v0
	s_mov_b64 s[0:1], s[62:63]
	v_ashrrev_i32_e32 v41, 31, v40
	v_lshlrev_b64 v[8:9], 12, v[40:41]
	v_and_b32_e32 v65, 63, v3
	v_lshl_add_u64 v[8:9], s[0:1], 0, v[8:9]
	s_mov_b64 s[0:1], s[62:63]
	s_mov_b64 s[2:3], s[62:63]
	v_lshlrev_b64 v[10:11], 9, v[40:41]
	v_lshlrev_b32_e32 v0, 3, v65
	v_lshl_add_u64 v[10:11], s[2:3], 0, v[10:11]
	v_lshl_add_u64 v[10:11], v[10:11], 0, v[0:1]
	v_add_co_u32_e32 v10, vcc, 0xe2c4000, v10
	v_and_b32_e32 v64, 15, v3
	s_nop 0
	v_addc_co_u32_e32 v11, vcc, 0, v11, vcc
	global_load_dwordx2 v[92:93], v[10:11], off
	s_waitcnt vmcnt(1)
	v_and_b32_e32 v56, 48, v3
	v_mov_b32_e32 v57, v1
	v_lshlrev_b32_e32 v0, 4, v64
	v_lshl_add_u64 v[8:9], v[8:9], 0, v[56:57]
	s_mov_b64 s[2:3], 0xe2d4000
	v_cmp_gt_u32_e32 vcc, 32, v65
	v_lshl_add_u64 v[42:43], v[8:9], 0, s[2:3]
	v_mov_b32_e32 v8, 0
	v_lshlrev_b32_e32 v0, 1, v0
	v_mov_b32_e32 v12, 0
	v_mov_b32_e32 v13, 0
	v_mov_b32_e32 v14, 0
	v_mov_b32_e32 v15, 0
	s_and_saveexec_b64 s[2:3], vcc
	s_cbranch_execz .LBB0_1747
	v_lshl_add_u64 v[10:11], v[42:43], 0, v[0:1]
	global_load_dwordx4 v[12:15], v[10:11], off sc0 sc1
.LBB0_1747:
	s_or_b64 exec, exec, s[2:3]
	v_mov_b32_e32 v9, 0
	v_mov_b32_e32 v10, 0
	v_mov_b32_e32 v11, 0
	s_and_saveexec_b64 s[2:3], vcc
	s_cbranch_execz .LBB0_1749
	v_lshl_add_u64 v[8:9], v[42:43], 0, v[0:1]
	global_load_dwordx4 v[8:11], v[8:9], off offset:512 sc0 sc1
.LBB0_1749:
	s_or_b64 exec, exec, s[2:3]
	v_mov_b32_e32 v16, 0
	v_mov_b32_e32 v20, 0
	v_mov_b32_e32 v21, 0
	v_mov_b32_e32 v22, 0
	v_mov_b32_e32 v23, 0
	s_and_saveexec_b64 s[2:3], vcc
	s_cbranch_execz .LBB0_1751
	v_lshl_add_u64 v[18:19], v[42:43], 0, v[0:1]
	global_load_dwordx4 v[20:23], v[18:19], off offset:1024 sc0 sc1
.LBB0_1751:
	s_or_b64 exec, exec, s[2:3]
	v_mov_b32_e32 v17, 0
	v_mov_b32_e32 v18, 0
	v_mov_b32_e32 v19, 0
	s_and_saveexec_b64 s[2:3], vcc
	s_cbranch_execz .LBB0_1753
	v_lshl_add_u64 v[16:17], v[42:43], 0, v[0:1]
	global_load_dwordx4 v[16:19], v[16:17], off offset:1536 sc0 sc1
.LBB0_1753:
	s_or_b64 exec, exec, s[2:3]
	v_mov_b32_e32 v24, 0
	v_mov_b32_e32 v28, 0
	v_mov_b32_e32 v29, 0
	v_mov_b32_e32 v30, 0
	v_mov_b32_e32 v31, 0
	s_and_saveexec_b64 s[2:3], vcc
	s_cbranch_execz .LBB0_1755
	v_lshl_add_u64 v[26:27], v[42:43], 0, v[0:1]
	global_load_dwordx4 v[28:31], v[26:27], off offset:2048 sc0 sc1
.LBB0_1755:
	s_or_b64 exec, exec, s[2:3]
	v_mov_b32_e32 v25, 0
	v_mov_b32_e32 v26, 0
	v_mov_b32_e32 v27, 0
	s_and_saveexec_b64 s[2:3], vcc
	s_cbranch_execz .LBB0_1757
	v_lshl_add_u64 v[24:25], v[42:43], 0, v[0:1]
	global_load_dwordx4 v[24:27], v[24:25], off offset:2560 sc0 sc1
.LBB0_1757:
	s_or_b64 exec, exec, s[2:3]
	v_mov_b32_e32 v32, 0
	v_mov_b32_e32 v36, 0
	v_mov_b32_e32 v37, 0
	v_mov_b32_e32 v38, 0
	v_mov_b32_e32 v39, 0
	s_and_saveexec_b64 s[2:3], vcc
	s_cbranch_execz .LBB0_1759
	v_lshl_add_u64 v[34:35], v[42:43], 0, v[0:1]
	global_load_dwordx4 v[36:39], v[34:35], off offset:3072 sc0 sc1
.LBB0_1759:
	s_or_b64 exec, exec, s[2:3]
	v_mov_b32_e32 v33, 0
	v_mov_b32_e32 v34, 0
	v_mov_b32_e32 v35, 0
	s_and_saveexec_b64 s[2:3], vcc
	s_cbranch_execz .LBB0_1761
	v_lshl_add_u64 v[32:33], v[42:43], 0, v[0:1]
	global_load_dwordx4 v[32:35], v[32:33], off offset:3584 sc0 sc1
.LBB0_1761:
	s_or_b64 exec, exec, s[2:3]
	v_bfe_u32 v57, v3, 4, 2
	v_lshlrev_b64 v[40:41], 11, v[40:41]
	v_lshlrev_b32_e32 v3, 3, v57
	v_lshl_add_u64 v[40:41], v[40:41], 1, s[0:1]
	v_lshlrev_b32_e32 v0, 8, v64
	v_lshl_add_u64 v[40:41], v[40:41], 0, v[0:1]
	v_lshlrev_b32_e32 v0, 1, v3
	v_lshl_add_u64 v[40:41], v[40:41], 0, v[0:1]
	s_mov_b64 s[0:1], 0xe354000
	v_add_co_u32_e32 v48, vcc, 0xe354000, v40
	v_lshl_add_u64 v[52:53], v[40:41], 0, s[0:1]
	s_nop 0
	v_addc_co_u32_e32 v49, vcc, 0, v41, vcc
	global_load_dwordx4 v[40:43], v[52:53], off offset:64 sc0 sc1
	global_load_dwordx4 v[44:47], v[52:53], off offset:128 sc0 sc1
	s_nop 0
	global_load_dwordx4 v[48:51], v[48:49], off sc0 sc1
	s_nop 0
	global_load_dwordx4 v[52:55], v[52:53], off offset:192 sc0 sc1
	v_readlane_b32 s0, v253, 62
	s_add_i32 s4, s4, s0
	s_ashr_i32 s0, s4, 4
	s_sub_i32 s1, s4, 64
	s_add_i32 s0, s0, 32
	s_lshr_b32 s1, s1, 4
	s_cmp_lt_i32 s4, 64
	s_cselect_b32 s0, s0, s1
	s_cmp_gt_i32 s0, 31
	s_cselect_b64 s[14:15], -1, 0
	s_cmp_lt_i32 s0, 32
	v_lshlrev_b32_e32 v58, 1, v65
	s_cselect_b64 s[2:3], -1, 0
	s_and_b64 vcc, exec, s[2:3]
	v_ashrrev_i32_e32 v3, 31, v2
	v_lshlrev_b32_e32 v94, 2, v58
	s_cbranch_vccnz .LBB0_1763
	s_sub_i32 s4, s0, 32
	s_lshl_b64 s[18:19], s[4:5], 2
	v_or_b32_e32 v58, s18, v114
	v_mov_b32_e32 v59, s19
	v_readlane_b32 s18, v255, 18
	s_mov_b64 s[16:17], s[68:69]
	v_lshlrev_b64 v[60:61], 9, v[2:3]
	v_or_b32_e32 v58, s18, v58
	v_lshlrev_b64 v[58:59], 14, v[58:59]
	v_lshl_add_u64 v[58:59], s[16:17], 0, v[58:59]
	v_lshl_add_u64 v[58:59], v[58:59], 0, v[60:61]
	v_mov_b32_e32 v95, v1
	v_lshl_add_u64 v[58:59], v[58:59], 0, v[94:95]
	global_load_dwordx2 v[112:113], v[58:59], off sc0 sc1
	v_readlane_b32 s19, v255, 19
	s_branch .LBB0_1764

.LBB0_1764:
	v_lshlrev_b32_e32 v58, 4, v2
	v_readlane_b32 s1, v255, 20
	v_readlane_b32 s36, v253, 34
	v_readlane_b32 s40, v253, 38
	v_add_u32_e32 v59, s1, v58
	v_readlane_b32 s41, v253, 39
	v_or_b32_e32 v60, v59, v64
	s_mov_b64 s[16:17], s[40:41]
	v_ashrrev_i32_e32 v61, 31, v60
	s_lshl_b32 s1, s0, 10
	v_lshl_add_u64 v[60:61], v[60:61], 2, s[16:17]
	global_load_dword v95, v[60:61], off
	s_lshl_b32 s4, s0, 8
	s_addk_i32 s1, 0xa000
	s_and_b64 s[16:17], s[14:15], exec
	s_cselect_b32 s16, s1, s4
	s_add_u32 s12, s12, 0x4680000
	s_addc_u32 s13, s13, 0
	v_readlane_b32 s37, v253, 35
	s_and_b64 s[14:15], s[14:15], exec
	s_cselect_b32 s1, 64, 16
	v_cmp_lt_u32_e64 s[36:37], 31, v65
	v_cmp_gt_u32_e32 vcc, 32, v65
	v_ashrrev_i32_e32 v59, 31, v58
	v_readlane_b32 s38, v253, 36
	v_readlane_b32 s39, v253, 37
	v_readlane_b32 s42, v253, 40
	v_readlane_b32 s43, v253, 41
	v_readlane_b32 s44, v253, 42
	v_readlane_b32 s45, v253, 43
	v_readlane_b32 s46, v253, 44
	v_readlane_b32 s47, v253, 45
	v_readlane_b32 s48, v253, 46
	v_readlane_b32 s49, v253, 47
	v_readlane_b32 s50, v253, 48
	v_readlane_b32 s51, v253, 49
	s_barrier
	s_and_saveexec_b64 s[14:15], vcc
	s_xor_b64 s[14:15], exec, s[14:15]
	s_cbranch_execz .LBB0_1766
	s_lshl_b32 s4, s1, 4
	s_add_i32 s4, s4, -16
	v_mov_b32_e32 v60, s4
	v_cmp_ne_u32_e32 vcc, 0, v114
	s_nop 1
	v_cndmask_b32_e32 v60, 0, v60, vcc
	v_add_u32_e32 v60, s16, v60
	v_or_b32_e32 v60, v60, v64
	v_ashrrev_i32_e32 v61, 31, v60
	v_lshlrev_b64 v[60:61], 12, v[60:61]
	v_lshl_add_u64 v[60:61], s[12:13], 0, v[60:61]
	v_lshl_add_u64 v[60:61], v[58:59], 1, v[60:61]
	v_lshl_add_u64 v[60:61], v[60:61], 0, v[0:1]
	global_load_dwordx4 v[60:63], v[60:61], off sc0 sc1

.LBB0_1773:
	s_add_i32 s15, s17, 1
	s_cmp_ge_u32 s15, s1
	s_cselect_b64 vcc, -1, 0
	s_waitcnt vmcnt(4)
	v_cndmask_b32_e32 v59, 0, v63, vcc
	s_nor_b64 s[12:13], s[36:37], vcc
	v_cndmask_b32_e32 v58, 0, v62, vcc
	v_cndmask_b32_e32 v57, 0, v61, vcc
	v_cndmask_b32_e32 v56, 0, v60, vcc
	s_and_saveexec_b64 s[8:9], s[12:13]
	s_cbranch_execz .LBB0_1775
	s_add_i32 s12, s14, -1
	v_mov_b32_e32 v56, s12
	v_mov_b32_e32 v57, s15
	v_cndmask_b32_e64 v56, v56, v57, s[38:39]
	v_lshl_add_u32 v56, v56, 4, v115
	v_ashrrev_i32_e32 v57, 31, v56
	v_lshlrev_b64 v[56:57], 12, v[56:57]
	v_lshl_add_u64 v[56:57], v[96:97], 0, v[56:57]
	global_load_dwordx4 v[56:59], v[56:57], off sc0 sc1

.LBB0_3314:
	v_readlane_b32 s2, v253, 13
	v_readlane_b32 s3, v253, 14
	v_readlane_b32 s6, v253, 17
	s_nop 3
	global_load_dword v0, v1, s[2:3] sc1
	v_readlane_b32 s2, v253, 3
	v_readlane_b32 s3, v253, 4
	s_waitcnt lgkmcnt(0)
	s_nop 3
	global_load_dword v2, v1, s[2:3] sc1
	v_readlane_b32 s2, v254, 2
	v_readlane_b32 s3, v254, 3
	s_nop 1
	s_nop 2
	global_load_dword v3, v1, s[2:3] sc1
	v_readlane_b32 s2, v254, 4
	v_readlane_b32 s3, v254, 5
	s_nop 1
	s_nop 2
	global_load_dword v8, v1, s[2:3] sc1
	v_readlane_b32 s2, v254, 6
	v_readlane_b32 s3, v254, 7
	s_nop 1
	s_nop 2
	global_load_dword v9, v1, s[2:3] sc1
	v_readlane_b32 s2, v254, 8
	v_readlane_b32 s3, v254, 9
	s_nop 1
	s_nop 2
	global_load_dword v10, v1, s[2:3] sc1
	v_readlane_b32 s2, v254, 10
	v_readlane_b32 s3, v254, 11
	s_nop 1
	s_nop 2
	global_load_dword v11, v1, s[2:3] sc1
	v_readlane_b32 s2, v254, 12
	v_readlane_b32 s3, v254, 13
	s_nop 1
	s_nop 2
	global_load_dword v12, v1, s[2:3] sc1
	v_readlane_b32 s2, v254, 14
	v_readlane_b32 s3, v254, 15
	s_nop 1
	s_nop 2
	global_load_dword v13, v1, s[2:3] sc1
	v_readlane_b32 s2, v254, 16
	v_readlane_b32 s3, v254, 17
	s_nop 1
	s_nop 2
	global_load_dword v14, v1, s[2:3] sc1
	v_readlane_b32 s2, v254, 18
	v_readlane_b32 s3, v254, 19
	s_nop 1
	s_nop 2
	global_load_dword v15, v1, s[2:3] sc1
	v_readlane_b32 s2, v254, 20
	v_readlane_b32 s3, v254, 21
	s_nop 1
	s_nop 2
	global_load_dword v16, v1, s[2:3] sc1
	v_readlane_b32 s2, v254, 22
	v_readlane_b32 s3, v254, 23
	s_nop 1
	s_nop 2
	global_load_dword v17, v1, s[2:3] sc1
	v_readlane_b32 s2, v254, 24
	v_readlane_b32 s3, v254, 25
	s_nop 1
	s_nop 2
	global_load_dword v18, v1, s[2:3] sc1
	v_readlane_b32 s2, v254, 26
	v_readlane_b32 s3, v254, 27
	s_nop 1
	s_nop 2
	global_load_dword v19, v1, s[2:3] sc1
	v_readlane_b32 s2, v254, 28
	v_readlane_b32 s3, v254, 29
	s_nop 1
	s_nop 2
	global_load_dword v20, v1, s[2:3] sc1
	s_mov_b64 s[2:3], -1
	s_waitcnt vmcnt(0)
	v_add_u32_e32 v21, v2, v0
	v_add_u32_e32 v21, v21, v3
	v_add_u32_e32 v21, v21, v8
	v_add_u32_e32 v21, v21, v9
	v_add_u32_e32 v21, v21, v10
	v_add_u32_e32 v21, v21, v11
	v_add_u32_e32 v21, v21, v12
	v_add_u32_e32 v21, v21, v13
	v_add_u32_e32 v21, v21, v14
	v_add_u32_e32 v21, v21, v15
	v_add_u32_e32 v21, v21, v16
	v_add_u32_e32 v21, v21, v17
	v_add_u32_e32 v21, v21, v18
	v_add_u32_e32 v21, v21, v19
	v_add_u32_e32 v21, v21, v20
	v_cmp_eq_u32_e32 vcc, s6, v21
	s_mov_b64 s[6:7], -1
	s_cbranch_vccnz .LBB0_3313
	s_and_b32 s2, s4, 0xff
	s_cmp_eq_u32 s2, 0
	s_mov_b64 s[2:3], -1
	s_mov_b64 s[8:9], -1
	s_sleep 1
	s_cbranch_scc1 .LBB0_3318
	s_and_b64 vcc, exec, s[8:9]
	s_cbranch_vccz .LBB0_3313
